# v23 + attention burst slot = (vcu>>3)%5: the 8 workgroups sharing a (batch, head) K/V burst at the same unit slot and stay in step
# baseline (speedup 1.0000x reference)
; #define LAS __attribute__((address_space(3)))
; __device__ __forceinline__ int lane_id() { int l; asm volatile("v_mbcnt_lo_u32_b32 %0, -1, 0\n\tv_mbcnt_hi_u32_b32 %0, -1, %0" : "=v"(l)); return l; }
; __global__ void __launch_bounds__(NWAVES * 64, 2) mk_fwd(Args args) {
;     ...
;             PH_ENTER();
;             const bf16* PROJ = (const bf16*)(ws + WS_PROJ); bf16* MIX = (bf16*)(ws + WS_MIX); bf16* DT = (bf16*)(ws + WS_DT);
;             const float* na_rpb = IN_(7); const float* sw_sink = IN_(10); const float* t5_table = IN_(13);
;             LAS float* tab = (LAS float*)(lds + att::OFF_TAB);
;             const int cslot = vcu % 5; int ui = 0;
;             for (int s = vcu; s < 1280; s += G, ++ui) {
;                 if (ui == cslot) {
;                     CArgs A2 = (CArgs)__builtin_amdgcn_kernarg_segment_ptr(); asm volatile("" : "+s"(A2)); unsigned char* ws2 = A2->ws;
;                     int wv2 = wave0; asm volatile("" : "+s"(wv2)); int ln2 = lane_id(); asm volatile("" : "+v"(ln2)); const int gw2 = vcu * NWAVES + wv2;
;                     const float* qsc = (const float*)(ws2 + WS_WQS) + 8;
;                     const ConvSrc cs{A2->in[5], A2->in[6], A2->in[14], A2->in[15], A2->in[1], A2->in[3]};
;                     conv_stream(cs, ws2, 0.f, qsc[3 * l + 1], qsc[3 * l + 2], (l + 1 < DEPTH) ? qsc[3 * l + 3] : 0.f, l, 1, 4, l + 1, 0, (l + 1 < DEPTH) ? 1 : 0, (((MTOK / 256) * (DIN / 256)) % G) ? CONV_TAIL_ITEMS : 0, 1 << 30, gw2, NGW, ln2); }
.LBB0_330:
	v_writelane_b32 v254, s4, 51
	s_add_i32 s1, s22, 1
	s_mov_b32 s10, 0
	v_writelane_b32 v254, s5, 52
	s_load_dwordx2 s[4:5], s[4:5], 0x88
	s_waitcnt lgkmcnt(0)
	v_writelane_b32 v254, s4, 53
	s_nop 1
	v_writelane_b32 v254, s5, 54
	s_mul_i32 s4, s22, 3
	s_mov_b32 s5, s13
	v_writelane_b32 v254, s4, 55
	s_nop 1
	v_writelane_b32 v254, s5, 56
	v_writelane_b32 v254, s1, 57
	s_xor_b32 s1, s22, 1
	v_writelane_b32 v254, s1, 58
	s_lshl_b32 s1, s2, 3
	v_writelane_b32 v254, s1, 59
	s_lshr_b32 s76, s26, 3
	s_mul_hi_i32 s1, s76, 0x66666667
	s_lshr_b32 s2, s1, 31
	s_ashr_i32 s1, s1, 1
	s_add_i32 s1, s1, s2
	s_mul_i32 s1, s1, 5
	s_sub_i32 s1, s76, s1
	v_writelane_b32 v254, s1, 60
	s_cmpk_gt_i32 s26, 0x4ff
	s_cbranch_scc1 .LBB0_520
	v_readlane_b32 s2, v254, 53
	v_readlane_b32 s3, v254, 54
	s_add_u32 s1, s2, 0x31800000
	v_writelane_b32 v254, s1, 61
	s_addc_u32 s1, s3, 0
	v_writelane_b32 v254, s1, 62
	s_add_u32 s1, s2, 0x3a800000
	v_writelane_b32 v254, s1, 63
	s_addc_u32 s1, s3, 0
	v_readlane_b32 s4, v254, 51
	v_readlane_b32 s5, v254, 52
	s_load_dwordx2 s[8:9], s[4:5], 0x38
	v_writelane_b32 v255, s1, 0
	s_add_u32 s1, s2, 0x52800000
	v_writelane_b32 v255, s1, 1
	s_addc_u32 s1, s3, 0
	v_readlane_b32 s2, v254, 50
	v_writelane_b32 v255, s1, 2
	s_abs_i32 s1, s2
	v_cvt_f32_u32_e32 v0, s1
	s_waitcnt lgkmcnt(0)
	v_writelane_b32 v255, s8, 3
	s_lshl_b32 s3, s22, 3
	s_lshl_b32 s2, s2, 4
	v_writelane_b32 v255, s9, 4
	s_load_dwordx2 s[8:9], s[4:5], 0x50
	v_rcp_iflag_f32_e32 v0, v0
	s_load_dwordx2 s[4:5], s[4:5], 0x68
	s_waitcnt lgkmcnt(0)
	v_writelane_b32 v255, s8, 5
	s_nop 1
	v_writelane_b32 v255, s9, 6
	v_writelane_b32 v255, s4, 7
	v_mul_f32_e32 v0, 0x4f7ffffe, v0
	v_cvt_u32_f32_e32 v0, v0
	v_writelane_b32 v255, s5, 8
	v_writelane_b32 v255, s3, 9
	v_readlane_b32 s3, v254, 48
	s_lshl_b32 s3, s3, 6
	s_nop 0
	v_writelane_b32 v255, s3, 10
	v_writelane_b32 v255, s2, 11
	s_sub_i32 s2, 0, s1
	v_readfirstlane_b32 s3, v0
	s_mul_i32 s2, s2, s3
	s_mul_hi_u32 s2, s3, s2
	s_add_i32 s3, s3, s2
	s_mul_hi_u32 s2, s3, 0x480
	s_mul_i32 s2, s2, s1
	s_sub_i32 s2, 0x480, s2
	s_sub_i32 s3, s2, s1
	s_cmp_ge_u32 s2, s1
	s_cselect_b32 s2, s3, s2
	s_sub_i32 s3, s2, s1
	s_cmp_ge_u32 s2, s1
	s_cselect_b32 s1, s3, s2
	s_cmp_eq_u32 s1, 0
	s_cselect_b32 s1, 0, 0x2000
	v_readlane_b32 s2, v254, 49
	s_add_i32 s1, s2, s1
	v_writelane_b32 v255, s1, 12
	s_branch .LBB0_333
